# XCD-local barriers in front of phases 2,6,7 (modulate->in-proj, out-proj0->modulate1->in-proj1 stay on one XCD), guarded by a run-time placement check with global fallback; dtype comment
# speedup vs baseline: 1.1148x; 1.0104x over previous
.LBB0_2:
	s_or_b64 exec, exec, s[2:3]
	s_load_dwordx4 s[76:79], s[0:1], 0xc0
	s_waitcnt lgkmcnt(0)
	s_add_u32 s2, s50, 0xf336000
	s_addc_u32 s3, s51, 0
	s_and_b32 s8, s4, 15
	s_sub_i32 s4, s77, s76
	s_cmp_gt_i32 s4, 1
	v_or_b32_e32 v1, s78, v175
	s_cselect_b64 s[4:5], -1, 0
	v_cmp_eq_u32_e32 vcc, 0, v1
	s_and_b64 s[6:7], vcc, s[4:5]
	s_barrier
	s_and_saveexec_b64 s[4:5], s[6:7]
	s_cbranch_execz .LBB0_5
	s_mov_b64 s[6:7], exec
	v_mbcnt_lo_u32_b32 v1, s6, 0
	v_mbcnt_hi_u32_b32 v1, s7, v1
	v_cmp_eq_u32_e32 vcc, 0, v1
	s_and_b64 s[10:11], exec, vcc
	s_mov_b64 exec, s[10:11]
	s_cbranch_execz .LBB0_5
	s_lshl_b32 s9, s8, 8
	s_bcnt1_i32_b64 s6, s[6:7]
	v_mov_b32_e32 v1, s9
	v_mov_b32_e32 v2, s6
	s_and_b32 s6, s73, 7
	s_lshl_b32 s6, 1, s6
	v_mov_b32_e32 v3, s6
	global_atomic_or v1, v3, s[2:3] offset:1028
	s_waitcnt vmcnt(0)
	global_atomic_add v1, v2, s[2:3] offset:1024

.LBB0_916:
	s_mov_b32 s101, 0
	buffer_inv sc1
	s_add_i32 s11, 0, 0x12ff0
	s_mov_b64 s[2:3], src_shared_base
	s_cmp_lg_u32 s11, -1
	s_cselect_b32 s2, s11, 0
	s_cselect_b32 s4, s3, 0
	s_add_i32 s10, 0, 0x12ff4
	s_cmp_lg_u32 s10, -1
	v_mov_b32_e32 v2, s2
	v_mov_b32_e32 v3, s4
	s_cselect_b32 s2, s10, 0
	s_cselect_b32 s3, s3, 0
	s_waitcnt vmcnt(0) expcnt(0) lgkmcnt(0)
	flat_load_dword v2, v[2:3] sc0 sc1
	s_waitcnt vmcnt(0)
	v_mov_b32_e32 v4, s2
	v_mov_b32_e32 v5, s3
	flat_load_dword v0, v[4:5] sc0 sc1
	s_waitcnt vmcnt(0) lgkmcnt(0)
	v_cmp_eq_u32_e32 vcc, 0, v2
	s_and_saveexec_b64 s[2:3], vcc
	s_cbranch_execz .LBB0_931
	v_readlane_b32 s6, v250, 4
	v_readlane_b32 s7, v250, 5
	s_load_dwordx2 s[4:5], s[6:7], 0x0
	s_nop 0
	s_load_dword s6, s[6:7], 0x8
	s_mov_b32 s13, 1
	s_waitcnt lgkmcnt(0)
	s_mul_i32 s12, s5, s4
	s_mul_i32 s12, s12, s6
	s_branch .LBB0_919

.LBB0_930:
	v_readlane_b32 s4, v251, 28
	v_readlane_b32 s5, v251, 29
	v_cmp_ne_u32_e32 vcc, 0, v0
	s_cmp_lg_u32 s11, -1
	v_cndmask_b32_e64 v17, 0, v0, s[4:5]
	v_readlane_b32 s4, v251, 26
	v_readlane_b32 s5, v251, 27
	v_cndmask_b32_e64 v0, 0, 1, vcc
	v_cmp_ne_u32_e32 vcc, 0, v2
	v_cndmask_b32_e64 v17, v17, v2, s[4:5]
	v_readlane_b32 s4, v251, 24
	v_readlane_b32 s5, v251, 25
	v_addc_co_u32_e32 v0, vcc, 0, v0, vcc
	s_nop 0
	v_cndmask_b32_e64 v17, v17, v3, s[4:5]
	v_readlane_b32 s4, v251, 22
	v_readlane_b32 s5, v251, 23
	v_cmp_ne_u32_e32 vcc, 0, v3
	s_cselect_b32 s6, s11, 0
	v_cndmask_b32_e64 v17, v17, v4, s[4:5]
	v_readlane_b32 s4, v251, 20
	v_readlane_b32 s5, v251, 21
	v_cndmask_b32_e64 v2, 0, 1, vcc
	v_cmp_ne_u32_e32 vcc, 0, v4
	v_cndmask_b32_e64 v17, v17, v5, s[4:5]
	v_readlane_b32 s4, v251, 18
	v_readlane_b32 s5, v251, 19
	v_addc_co_u32_e32 v0, vcc, v0, v2, vcc
	s_nop 0
	v_cndmask_b32_e64 v17, v17, v6, s[4:5]
	v_readlane_b32 s4, v251, 16
	v_readlane_b32 s5, v251, 17
	v_cmp_ne_u32_e32 vcc, 0, v5
	v_mov_b32_e32 v4, s6
	v_cndmask_b32_e64 v17, v17, v7, s[4:5]
	v_readlane_b32 s4, v251, 14
	v_readlane_b32 s5, v251, 15
	v_cndmask_b32_e64 v2, 0, 1, vcc
	v_cmp_ne_u32_e32 vcc, 0, v6
	v_cndmask_b32_e64 v17, v17, v8, s[4:5]
	v_readlane_b32 s4, v251, 12
	v_readlane_b32 s5, v251, 13
	v_addc_co_u32_e32 v0, vcc, v0, v2, vcc
	s_nop 0
	v_cndmask_b32_e64 v17, v17, v9, s[4:5]
	v_readlane_b32 s4, v251, 10
	v_readlane_b32 s5, v251, 11
	v_cmp_ne_u32_e32 vcc, 0, v7
	s_nop 0
	v_cndmask_b32_e64 v17, v17, v10, s[4:5]
	v_readlane_b32 s4, v251, 8
	v_readlane_b32 s5, v251, 9
	v_cndmask_b32_e64 v2, 0, 1, vcc
	v_cmp_ne_u32_e32 vcc, 0, v8
	v_cndmask_b32_e64 v17, v17, v11, s[4:5]
	v_readlane_b32 s4, v251, 6
	v_addc_co_u32_e32 v0, vcc, v0, v2, vcc
	v_readlane_b32 s5, v251, 7
	v_cmp_ne_u32_e32 vcc, 0, v9
	s_nop 0
	v_cndmask_b32_e64 v17, v17, v12, s[4:5]
	v_readlane_b32 s4, v251, 4
	v_cndmask_b32_e64 v2, 0, 1, vcc
	v_cmp_ne_u32_e32 vcc, 0, v10
	v_readlane_b32 s5, v251, 5
	s_nop 0
	v_addc_co_u32_e32 v0, vcc, v0, v2, vcc
	v_cndmask_b32_e64 v17, v17, v13, s[4:5]
	v_readlane_b32 s4, v251, 2
	v_cmp_ne_u32_e32 vcc, 0, v11
	v_readlane_b32 s5, v251, 3
	s_nop 0
	v_cndmask_b32_e64 v2, 0, 1, vcc
	v_cmp_ne_u32_e32 vcc, 0, v12
	v_cndmask_b32_e64 v17, v17, v14, s[4:5]
	v_readlane_b32 s4, v251, 0
	v_addc_co_u32_e32 v0, vcc, v0, v2, vcc
	v_readlane_b32 s5, v251, 1
	v_cmp_ne_u32_e32 vcc, 0, v13
	s_nop 0
	v_cndmask_b32_e64 v17, v17, v15, s[4:5]
	v_readlane_b32 s4, v250, 62
	v_cndmask_b32_e64 v2, 0, 1, vcc
	v_cmp_ne_u32_e32 vcc, 0, v14
	v_readlane_b32 s5, v250, 63
	s_nop 0
	v_addc_co_u32_e32 v0, vcc, v0, v2, vcc
	v_cndmask_b32_e64 v17, v17, v16, s[4:5]
	v_cmp_ne_u32_e32 vcc, 0, v15
	s_mov_b64 s[4:5], src_shared_base
	s_cselect_b32 s4, s5, 0
	v_cndmask_b32_e64 v2, 0, 1, vcc
	v_cmp_ne_u32_e32 vcc, 0, v16
	s_cmp_lg_u32 s10, -1
	v_mov_b32_e32 v5, s4
	v_addc_co_u32_e32 v0, vcc, v0, v2, vcc
	v_max_u32_e32 v2, 1, v17
	s_cselect_b32 s4, s10, 0
	s_cselect_b32 s5, s5, 0
	v_max_u32_e32 v0, 1, v0
	flat_store_dword v[4:5], v2 sc0 sc1
	s_waitcnt vmcnt(0)
	v_mov_b32_e32 v4, s4
	v_mov_b32_e32 v5, s5
	flat_store_dword v[4:5], v0 sc0 sc1
	s_waitcnt vmcnt(0)
	v_readlane_b32 s4, v250, 30
	v_readlane_b32 s5, v250, 31
	s_nop 4
	global_load_dword v7, v1, s[4:5] offset:4 sc1
	v_readlane_b32 s4, v250, 32
	v_readlane_b32 s5, v250, 33
	s_nop 4
	global_load_dword v8, v1, s[4:5] offset:4 sc1
	v_readlane_b32 s4, v250, 34
	v_readlane_b32 s5, v250, 35
	s_nop 4
	global_load_dword v9, v1, s[4:5] offset:4 sc1
	v_readlane_b32 s4, v250, 36
	v_readlane_b32 s5, v250, 37
	s_nop 4
	global_load_dword v10, v1, s[4:5] offset:4 sc1
	v_readlane_b32 s4, v250, 38
	v_readlane_b32 s5, v250, 39
	s_nop 4
	global_load_dword v12, v1, s[4:5] offset:4 sc1
	v_readlane_b32 s4, v250, 40
	v_readlane_b32 s5, v250, 41
	s_nop 4
	global_load_dword v13, v1, s[4:5] offset:4 sc1
	v_readlane_b32 s4, v250, 42
	v_readlane_b32 s5, v250, 43
	s_nop 4
	global_load_dword v14, v1, s[4:5] offset:4 sc1
	v_readlane_b32 s4, v250, 44
	v_readlane_b32 s5, v250, 45
	s_nop 4
	global_load_dword v15, v1, s[4:5] offset:4 sc1
	s_mov_b32 s101, 1

.LBB0_933:
	s_or_b64 exec, exec, s[2:3]
	s_waitcnt vmcnt(0)
	s_cmp_eq_u32 s101, 0
	s_cbranch_scc1 .Lxb_noflag
	v_mov_b32_e32 v11, 0
	v_mov_b32_e32 v16, 0
	v_mov_b32_e32 v17, 0
	v_or_b32_e32 v11, v11, v7
	v_cmp_ne_u32_e32 vcc, 0, v7
	v_addc_co_u32_e32 v17, vcc, 0, v17, vcc
	v_add_u32_e32 v5, -1, v7
	v_and_b32_e32 v5, v5, v7
	v_or_b32_e32 v16, v16, v5
	v_or_b32_e32 v11, v11, v8
	v_cmp_ne_u32_e32 vcc, 0, v8
	v_addc_co_u32_e32 v17, vcc, 0, v17, vcc
	v_add_u32_e32 v5, -1, v8
	v_and_b32_e32 v5, v5, v8
	v_or_b32_e32 v16, v16, v5
	v_or_b32_e32 v11, v11, v9
	v_cmp_ne_u32_e32 vcc, 0, v9
	v_addc_co_u32_e32 v17, vcc, 0, v17, vcc
	v_add_u32_e32 v5, -1, v9
	v_and_b32_e32 v5, v5, v9
	v_or_b32_e32 v16, v16, v5
	v_or_b32_e32 v11, v11, v10
	v_cmp_ne_u32_e32 vcc, 0, v10
	v_addc_co_u32_e32 v17, vcc, 0, v17, vcc
	v_add_u32_e32 v5, -1, v10
	v_and_b32_e32 v5, v5, v10
	v_or_b32_e32 v16, v16, v5
	v_or_b32_e32 v11, v11, v12
	v_cmp_ne_u32_e32 vcc, 0, v12
	v_addc_co_u32_e32 v17, vcc, 0, v17, vcc
	v_add_u32_e32 v5, -1, v12
	v_and_b32_e32 v5, v5, v12
	v_or_b32_e32 v16, v16, v5
	v_or_b32_e32 v11, v11, v13
	v_cmp_ne_u32_e32 vcc, 0, v13
	v_addc_co_u32_e32 v17, vcc, 0, v17, vcc
	v_add_u32_e32 v5, -1, v13
	v_and_b32_e32 v5, v5, v13
	v_or_b32_e32 v16, v16, v5
	v_or_b32_e32 v11, v11, v14
	v_cmp_ne_u32_e32 vcc, 0, v14
	v_addc_co_u32_e32 v17, vcc, 0, v17, vcc
	v_add_u32_e32 v5, -1, v14
	v_and_b32_e32 v5, v5, v14
	v_or_b32_e32 v16, v16, v5
	v_or_b32_e32 v11, v11, v15
	v_cmp_ne_u32_e32 vcc, 0, v15
	v_addc_co_u32_e32 v17, vcc, 0, v17, vcc
	v_add_u32_e32 v5, -1, v15
	v_and_b32_e32 v5, v5, v15
	v_or_b32_e32 v16, v16, v5
	v_cmp_eq_u32_e32 vcc, 0xff, v11
	v_cndmask_b32_e64 v14, 0, 1, vcc
	v_cmp_eq_u32_e32 vcc, 8, v17
	v_cndmask_b32_e64 v15, 0, 1, vcc
	v_and_b32_e32 v14, v14, v15
	v_cmp_eq_u32_e32 vcc, 0, v16
	v_cndmask_b32_e64 v15, 0, 1, vcc
	v_and_b32_e32 v14, v14, v15
	v_cmp_eq_u32_e32 vcc, 8, v0
	v_cndmask_b32_e64 v15, 0, 1, vcc
	v_and_b32_e32 v14, v14, v15
	s_mov_b64 s[4:5], src_shared_base
	v_mov_b32_e32 v12, 0x12ff8
	v_mov_b32_e32 v13, s5
	flat_store_dword v[12:13], v14 sc0 sc1
	s_waitcnt vmcnt(0) lgkmcnt(0)
.Lxb_noflag:
	v_readfirstlane_b32 s2, v4
	v_sub_u32_e32 v5, 0, v2
	s_nop 0
	v_add_u32_e32 v4, s2, v3
	v_cvt_f32_u32_e32 v3, v2
	v_rcp_iflag_f32_e32 v3, v3
	s_nop 0
	v_mul_f32_e32 v3, 0x4f7ffffe, v3
	v_cvt_u32_f32_e32 v3, v3
	v_mul_lo_u32 v5, v5, v3
	v_mul_hi_u32 v5, v3, v5
	v_add_u32_e32 v3, v3, v5
	v_mul_hi_u32 v3, v4, v3
	v_mul_lo_u32 v5, v3, v2
	v_sub_u32_e32 v5, v4, v5
	v_cmp_ge_u32_e32 vcc, v5, v2
	v_add_u32_e32 v6, 1, v3
	s_nop 0
	v_cndmask_b32_e32 v3, v3, v6, vcc
	v_sub_u32_e32 v6, v5, v2
	v_cndmask_b32_e32 v5, v5, v6, vcc
	v_cmp_ge_u32_e32 vcc, v5, v2
	v_add_u32_e32 v5, 1, v3
	v_add_u32_e32 v6, 1, v4
	v_cndmask_b32_e32 v3, v3, v5, vcc
	v_mad_u64_u32 v[4:5], s[2:3], v2, v3, v[2:3]
	v_cmp_ne_u32_e32 vcc, v6, v4
	s_and_saveexec_b64 s[2:3], vcc
	s_xor_b64 s[2:3], exec, s[2:3]
	s_cbranch_execz .LBB0_947
	v_readlane_b32 s4, v251, 32
	v_readlane_b32 s5, v251, 33
	s_nop 4
	global_load_dword v0, v1, s[4:5] sc1
	s_waitcnt vmcnt(0)
	v_cmp_eq_u32_e32 vcc, v0, v3
	s_and_saveexec_b64 s[4:5], vcc
	s_cbranch_execz .LBB0_946
	s_mov_b32 s16, 1
	s_mov_b64 s[6:7], 0
	s_branch .LBB0_937

.LBB0_948:
	s_mov_b64 s[2:3], exec
	s_cmp_eq_u32 s76, 2
	s_cbranch_scc1 .Lxb_maybe_local
	s_cmp_eq_u32 s76, 6
	s_cbranch_scc1 .Lxb_maybe_local
	s_cmp_eq_u32 s76, 7
	s_cbranch_scc0 .Lxb_global
.Lxb_maybe_local:
	s_mov_b64 s[4:5], src_shared_base
	v_mov_b32_e32 v4, 0x12ff8
	v_mov_b32_e32 v5, s5
	flat_load_dword v5, v[4:5] sc0 sc1
	s_waitcnt vmcnt(0) lgkmcnt(0)
	v_readfirstlane_b32 s4, v5
	s_cmp_lg_u32 s4, 0
	s_cbranch_scc1 .Lxb_local
.Lxb_global:
	buffer_wbl2 sc1
	s_waitcnt lgkmcnt(0)
	s_waitcnt vmcnt(0)
	v_mbcnt_lo_u32_b32 v2, s2, 0
	v_mbcnt_hi_u32_b32 v2, s3, v2
	v_cmp_eq_u32_e32 vcc, 0, v2
	s_and_saveexec_b64 s[4:5], vcc
	s_cbranch_execz .LBB0_950
	s_bcnt1_i32_b64 s2, s[2:3]
	v_mov_b32_e32 v3, s2
	v_readlane_b32 s2, v251, 34
	v_readlane_b32 s3, v251, 35
	s_nop 4
	global_atomic_add v3, v1, v3, s[2:3] sc0

.Lxb_local:
	s_mov_b64 s[2:3], exec
	v_mbcnt_lo_u32_b32 v0, s2, 0
	v_mbcnt_hi_u32_b32 v0, s3, v0
	v_cmp_eq_u32_e32 vcc, 0, v0
	s_waitcnt vmcnt(0)
	s_and_saveexec_b64 s[4:5], vcc
	s_cbranch_execnz .LBB0_965
	s_getpc_b64 s[98:99]
